# FFN-down tail: 16 context filter items moved to GEMM-unit owners, ffn2 gate/up weight copies split over all 256 workgroups; plus norm prefetch waits and MFMA chain order
# speedup vs baseline: 1.0165x; 1.0165x over previous
.LBB0_346:
	s_mul_hi_u32 s6, s77, 0x280
	s_mul_i32 s6, s6, s76
	s_sub_i32 s6, 0x280, s6
	s_sub_i32 s7, s6, s76
	s_cmp_ge_u32 s6, s76
	s_cselect_b32 s6, s7, s6
	s_sub_i32 s7, s6, s76
	s_cmp_ge_u32 s6, s76
	s_cselect_b32 s74, s7, s6
	s_sub_i32 s10, s42, s74
	s_cmp_lt_i32 s2, s74
	s_cselect_b64 s[6:7], -1, 0
	s_and_b64 s[8:9], s[6:7], exec
	s_cselect_b32 s10, 0, s10
	s_cmp_eq_u32 s74, 0
	s_waitcnt lgkmcnt(0)
	s_cselect_b64 s[24:25], -1, 0
	s_and_b64 s[8:9], s[24:25], exec
	s_cselect_b32 s44, s42, s10
	s_sub_i32 s100, s2, s74
	s_cmp_lt_i32 s2, s74
	s_cselect_b32 s100, 0, s100
	s_cmp_eq_u32 s74, 0
	s_cselect_b32 s100, s2, s100
	s_mov_b32 s101, s44
	s_movk_i32 s99, 0x10f
	s_cmpk_lg_i32 s42, 0x100
	s_cbranch_scc1 .Lfilt_generic
	s_movk_i32 s101, 0x80
	s_cmpk_lt_i32 s2, 0x80
	s_cbranch_scc0 .Lfilt_worker
	s_add_i32 s100, s2, 0x100
	s_branch .Lfilt_go
.Lfilt_worker:
	s_movk_i32 s99, 0xff
	s_branch .Lfilt_go

.Lfilt_go:
	s_sub_i32 s8, s2, s74
	s_and_b64 s[6:7], s[6:7], exec
	s_cselect_b32 s8, 0, s8
	s_and_b64 s[6:7], s[24:25], exec
	s_cselect_b32 s47, s2, s8
	s_cmp_gt_i32 s100, s99
	s_cbranch_scc1 .Lfilt_copies
	v_lshl_add_u64 v[10:11], s[12:13], 0, v[200:201]
	s_mov_b64 s[8:9], 0x100
	v_mov_b32_e32 v3, 0
	v_mov_b32_e32 v2, v200
	v_lshl_add_u64 v[10:11], v[10:11], 0, s[8:9]
	v_lshrrev_b32_e32 v37, 6, v218
	s_movk_i32 s8, 0x84
	s_movk_i32 s6, 0x210
	v_lshl_add_u64 v[4:5], s[14:15], 0, v[2:3]
	v_lshl_add_u64 v[6:7], s[30:31], 0, v[2:3]
	v_lshl_add_u64 v[8:9], s[18:19], 0, v[2:3]
	v_lshlrev_b32_e32 v2, 2, v218
	v_mad_u32_u24 v38, v37, s8, 16
	v_lshl_add_u64 v[12:13], s[16:17], 0, v[200:201]
	s_mov_b64 s[8:9], 0x200
	v_cmp_gt_u32_e64 s[6:7], s6, v218
	v_add_u32_e32 v36, 16, v2
	v_lshl_add_u64 v[12:13], v[12:13], 0, s[8:9]
	v_lshl_add_u64 v[14:15], s[28:29], 0, v[2:3]
	s_mov_b32 s15, 0
	v_mov_b32_e32 v39, 0x38d1b717
	s_brev_b32 s50, 18
	s_mov_b32 s51, 0xfe5163ab
	s_mov_b32 s56, 0x3c439041
	s_mov_b32 s57, 0xdb629599
	s_mov_b32 s58, 0xf534ddc0
	s_mov_b32 s59, 0xfc2757d1
	s_mov_b32 s60, 0x4e441529
	s_mov_b32 s61, 0xa2f9836e
	s_mov_b32 s62, 0x3fc90fda
	s_mov_b32 s63, 0x3f22f983
	s_mov_b32 s64, 0xbfc90fda
	v_mov_b32_e32 v40, 0x3c0881c4
	v_mov_b32_e32 v41, 0xbab64f3b
	s_movk_i32 s65, 0x1f8
	s_movk_i32 s66, 0x1ff
	s_add_i32 s67, 16, 0x840
	v_mov_b32_e32 v42, 0x40447cbd
	v_not_b32_e32 v43, 63
	v_not_b32_e32 v44, 31
	v_mov_b32_e32 v45, 0xffc00000
	v_mov_b32_e32 v46, 0x7fc00000
	s_mov_b32 s68, s100
	s_branch .LBB0_350
.LBB0_349:
	s_add_i32 s68, s68, s101
	s_cmp_gt_i32 s68, s99
	s_cbranch_scc1 .Lfilt_copies

.Lfilt_copies:
	s_cmpk_lg_i32 s42, 0x100
	s_cbranch_scc1 .Lfilt_copies_generic
	s_mov_b32 s47, s2
	s_movk_i32 s44, 0x100
	s_branch .LBB0_395
